# v28 + grid barrier: XCD leaders poll the monotonic cross-XCD arrival counter instead of waiting for the atomic's return and a separate release word
# speedup vs baseline: 1.0021x; 1.0021x over previous
.LBB0_550:
	s_andn2_saveexec_b64 s[4:5], s[4:5]
	s_cbranch_execz .LBB0_568
	s_mov_b64 s[4:5], exec
	buffer_wbl2 sc1
	s_waitcnt lgkmcnt(0)
	s_waitcnt vmcnt(0)
	v_readlane_b32 s6, v253, 52
	v_readlane_b32 s7, v253, 53
	v_add_u32_e32 v2, 1, v1
	v_mul_lo_u32 v2, v2, v0
	v_mov_b32_e32 v3, 1
	s_nop 1
	global_atomic_add v64, v3, s[6:7]
.Lxt_spin0:
	global_load_dword v3, v64, s[6:7] sc1
	s_waitcnt vmcnt(0)
	v_cmp_lt_u32_e32 vcc, v3, v2
	s_cbranch_vccz .Lxt_done0
	s_sleep 1
	s_branch .Lxt_spin0
.Lxt_done0:
	s_mov_b64 s[4:5], exec
	s_mov_b64 s[6:7], 0

.LBB0_1456:
	s_mov_b64 s[4:5], exec
	buffer_wbl2 sc1
	s_waitcnt lgkmcnt(0)
	s_waitcnt vmcnt(0)
	v_readlane_b32 s6, v253, 52
	v_readlane_b32 s7, v253, 53
	v_add_u32_e32 v2, 1, v1
	v_mul_lo_u32 v2, v2, v0
	v_mov_b32_e32 v3, 1
	s_nop 1
	global_atomic_add v64, v3, s[6:7]
